# closed-form next-tile index also in the W_in and W_out GEMMs
# baseline (speedup 1.0000x reference)
.LBB0_114:
	s_andn2_b64 vcc, exec, s[44:45]
	s_cbranch_vccnz .LBB0_118
	s_cmp_gt_u32 s47, 8
	s_mov_b64 s[62:63], 0
	s_cbranch_scc1 .LBB0_117
	s_lshl_b32 s45, s49, 5
	s_and_b32 s45, s45, 0xc0
	s_add_i32 s45, s45, s2
	s_lshl_b32 s44, s49, 8
	s_and_b32 s45, s45, 0xc0
	s_or_b32 s44, s45, s44
	v_readlane_b32 s45, v253, 59
	s_or_b32 s44, s44, s45
	s_lshr_b32 s44, s44, 3
	v_readlane_b32 s45, v254, 25
	s_add_i32 s45, s44, s45
	s_lshr_b32 s45, s45, 3
	s_and_b32 s46, s45, 0x1ff8
	s_and_b32 s54, s44, 63
	s_mov_b64 s[62:63], -1
	s_lshr_b32 s58, s54, 3
	s_and_b32 s44, s54, 7
	s_add_i32 s46, s46, s44

.LBB0_351:
	s_add_i32 s71, s71, 1
	s_mul_i32 s38, s71, s70
	s_mul_hi_u32 s39, s71, s3
	s_add_i32 s39, s39, s38
	s_mul_i32 s38, s71, s3
	s_add_u32 s50, s38, s2
	s_addc_u32 s51, s39, s73
	v_mov_b64_e32 v[0:1], 0x500
	v_cmp_lt_i64_e64 s[38:39], s[50:51], v[0:1]
	v_mov_b64_e32 v[0:1], 0x4ff
	v_cmp_gt_i64_e32 vcc, s[50:51], v[0:1]
	s_cbranch_vccnz .LBB0_353
	s_and_b32 s47, s50, 7
	s_lshr_b32 s49, s50, 3
	s_mul_i32 s47, s47, 0xa0
	s_add_i32 s47, s47, s49
	s_bfe_u32 s46, s47, 0x20003
	s_lshr_b32 s49, s47, 5
	s_lshl_b32 s49, s49, 3
	s_and_b32 s47, s47, 7
	s_add_i32 s48, s49, s47
